# ctx attention: the 8 K-fragment LDS reads batched into distinct register quads (counted lgkmcnt), on top of the previous stack
# baseline (speedup 1.0000x reference)
.LBB0_675:
	v_add_u32_e32 v2, s8, v150
	ds_read_b128 v[4:7], v2
	ds_read_b128 v[158:161], v2 offset:4608
	ds_read_b128 v[162:165], v2 offset:32
	ds_read_b128 v[180:183], v2 offset:4640
	ds_read_b128 v[184:187], v2 offset:64
	ds_read_b128 v[188:191], v2 offset:4672
	ds_read_b128 v[192:195], v2 offset:96
	ds_read_b128 v[196:199], v2 offset:4704
	s_mov_b32 s2, 0x41000000
	s_waitcnt vmcnt(11) lgkmcnt(7)
	v_mfma_f32_32x32x16_bf16 v[66:81], v[4:7], v[106:109], 0
	s_waitcnt lgkmcnt(6)
	v_mfma_f32_32x32x16_bf16 v[50:65], v[158:161], v[106:109], 0
	s_waitcnt vmcnt(10) lgkmcnt(5)
	v_mfma_f32_32x32x16_bf16 v[66:81], v[162:165], v[110:113], v[66:81]
	s_waitcnt lgkmcnt(4)
	v_mfma_f32_32x32x16_bf16 v[50:65], v[180:183], v[110:113], v[50:65]
	s_waitcnt vmcnt(9) lgkmcnt(3)
	v_mfma_f32_32x32x16_bf16 v[66:81], v[184:187], v[114:117], v[66:81]
	s_waitcnt lgkmcnt(2)
	v_mfma_f32_32x32x16_bf16 v[50:65], v[188:191], v[114:117], v[50:65]
	s_waitcnt vmcnt(8) lgkmcnt(1)
	v_mfma_f32_32x32x16_bf16 v[66:81], v[192:195], v[118:121], v[66:81]
	s_waitcnt lgkmcnt(0)
	v_mfma_f32_32x32x16_bf16 v[50:65], v[196:199], v[118:121], v[50:65]
	s_nop 8
	v_max3_f32 v2, v66, v67, v68
	v_max3_f32 v2, v2, v69, v70
	v_max3_f32 v2, v2, v71, v72
	v_max3_f32 v2, v2, v73, v74
	v_max3_f32 v2, v2, v75, v76
	v_max3_f32 v2, v2, v77, v78
	v_max3_f32 v2, v2, v79, v80
	v_max_f32_e32 v4, v51, v51
	v_max_f32_e32 v5, v50, v50
	v_max_f32_e32 v4, v5, v4
	v_max3_f32 v4, v4, v52, v53
	v_max3_f32 v4, v4, v54, v55
	v_max3_f32 v4, v4, v56, v57
	v_max3_f32 v4, v4, v58, v59
	v_max3_f32 v4, v4, v60, v61
	v_max3_f32 v4, v4, v62, v63
	v_max3_f32 v4, v4, v64, v65
	v_max3_f32 v2, v2, v81, v4
	ds_bpermute_b32 v4, v208, v2
	s_waitcnt lgkmcnt(0)
	v_max_f32_e32 v4, v4, v4
	v_max_f32_e32 v2, v2, v4
	v_fma_f32 v4, v2, s30, -v135
	v_cmp_lt_f32_e32 vcc, s2, v4
	s_cbranch_vccz .LBB0_674
	v_mul_f32_e32 v2, 0x3e38aa3b, v2
	v_max_f32_e32 v2, v2, v2
	v_max_f32_e32 v4, v135, v135
	v_max_f32_e32 v4, v4, v2
	v_sub_f32_e32 v2, v135, v4
	v_exp_f32_e32 v2, v2
	v_mov_b32_e32 v135, v4
	v_mul_f32_e32 v133, v133, v2
	v_pk_mul_f32 v[48:49], v[48:49], v[2:3] op_sel_hi:[1,0]
	v_pk_mul_f32 v[46:47], v[46:47], v[2:3] op_sel_hi:[1,0]
	v_pk_mul_f32 v[44:45], v[44:45], v[2:3] op_sel_hi:[1,0]
	v_pk_mul_f32 v[42:43], v[42:43], v[2:3] op_sel_hi:[1,0]
	v_pk_mul_f32 v[40:41], v[40:41], v[2:3] op_sel_hi:[1,0]
	v_pk_mul_f32 v[38:39], v[38:39], v[2:3] op_sel_hi:[1,0]
	v_pk_mul_f32 v[36:37], v[36:37], v[2:3] op_sel_hi:[1,0]
	v_pk_mul_f32 v[34:35], v[34:35], v[2:3] op_sel_hi:[1,0]
	v_pk_mul_f32 v[32:33], v[32:33], v[2:3] op_sel_hi:[1,0]
	v_pk_mul_f32 v[30:31], v[30:31], v[2:3] op_sel_hi:[1,0]
	v_pk_mul_f32 v[28:29], v[28:29], v[2:3] op_sel_hi:[1,0]
	v_pk_mul_f32 v[26:27], v[26:27], v[2:3] op_sel_hi:[1,0]
	v_pk_mul_f32 v[24:25], v[24:25], v[2:3] op_sel_hi:[1,0]
	v_pk_mul_f32 v[22:23], v[22:23], v[2:3] op_sel_hi:[1,0]
	v_pk_mul_f32 v[20:21], v[20:21], v[2:3] op_sel_hi:[1,0]
	v_pk_mul_f32 v[18:19], v[18:19], v[2:3] op_sel_hi:[1,0]
	s_branch .LBB0_674

.LBB0_681:
	v_add_u32_e32 v2, s1, v150
	ds_read_b128 v[4:7], v2
	ds_read_b128 v[158:161], v2 offset:4608
	ds_read_b128 v[162:165], v2 offset:32
	ds_read_b128 v[180:183], v2 offset:4640
	ds_read_b128 v[184:187], v2 offset:64
	ds_read_b128 v[188:191], v2 offset:4672
	ds_read_b128 v[192:195], v2 offset:96
	ds_read_b128 v[196:199], v2 offset:4704
	s_mov_b32 s2, 0x41000000
	s_waitcnt vmcnt(3) lgkmcnt(7)
	v_mfma_f32_32x32x16_bf16 v[66:81], v[4:7], v[106:109], 0
	s_waitcnt lgkmcnt(6)
	v_mfma_f32_32x32x16_bf16 v[50:65], v[158:161], v[106:109], 0
	s_waitcnt vmcnt(2) lgkmcnt(5)
	v_mfma_f32_32x32x16_bf16 v[66:81], v[162:165], v[110:113], v[66:81]
	s_waitcnt lgkmcnt(4)
	v_mfma_f32_32x32x16_bf16 v[50:65], v[180:183], v[110:113], v[50:65]
	s_waitcnt vmcnt(1) lgkmcnt(3)
	v_mfma_f32_32x32x16_bf16 v[66:81], v[184:187], v[114:117], v[66:81]
	s_waitcnt lgkmcnt(2)
	v_mfma_f32_32x32x16_bf16 v[50:65], v[188:191], v[114:117], v[50:65]
	s_waitcnt vmcnt(0) lgkmcnt(1)
	v_mfma_f32_32x32x16_bf16 v[66:81], v[192:195], v[118:121], v[66:81]
	s_waitcnt lgkmcnt(0)
	v_mfma_f32_32x32x16_bf16 v[50:65], v[196:199], v[118:121], v[50:65]
	s_nop 8
	v_max3_f32 v2, v66, v67, v68
	v_max3_f32 v2, v2, v69, v70
	v_max3_f32 v2, v2, v71, v72
	v_max3_f32 v2, v2, v73, v74
	v_max3_f32 v2, v2, v75, v76
	v_max3_f32 v2, v2, v77, v78
	v_max3_f32 v2, v2, v79, v80
	v_max_f32_e32 v4, v51, v51
	v_max_f32_e32 v5, v50, v50
	v_max_f32_e32 v4, v5, v4
	v_max3_f32 v4, v4, v52, v53
	v_max3_f32 v4, v4, v54, v55
	v_max3_f32 v4, v4, v56, v57
	v_max3_f32 v4, v4, v58, v59
	v_max3_f32 v4, v4, v60, v61
	v_max3_f32 v4, v4, v62, v63
	v_max3_f32 v4, v4, v64, v65
	v_max3_f32 v2, v2, v81, v4
	ds_bpermute_b32 v4, v208, v2
	s_waitcnt lgkmcnt(0)
	v_max_f32_e32 v4, v4, v4
	v_max_f32_e32 v2, v2, v4
	v_fma_f32 v4, v2, s30, -v84
	v_cmp_lt_f32_e32 vcc, s2, v4
	s_cbranch_vccz .LBB0_680
	v_mul_f32_e32 v2, 0x3e38aa3b, v2
	v_max_f32_e32 v2, v2, v2
	v_max_f32_e32 v4, v84, v84
	v_max_f32_e32 v4, v4, v2
	v_sub_f32_e32 v2, v84, v4
	v_exp_f32_e32 v2, v2
	v_mov_b32_e32 v84, v4
	v_mul_f32_e32 v83, v83, v2
	v_pk_mul_f32 v[48:49], v[48:49], v[2:3] op_sel_hi:[1,0]
	v_pk_mul_f32 v[46:47], v[46:47], v[2:3] op_sel_hi:[1,0]
	v_pk_mul_f32 v[44:45], v[44:45], v[2:3] op_sel_hi:[1,0]
	v_pk_mul_f32 v[42:43], v[42:43], v[2:3] op_sel_hi:[1,0]
	v_pk_mul_f32 v[40:41], v[40:41], v[2:3] op_sel_hi:[1,0]
	v_pk_mul_f32 v[38:39], v[38:39], v[2:3] op_sel_hi:[1,0]
	v_pk_mul_f32 v[36:37], v[36:37], v[2:3] op_sel_hi:[1,0]
	v_pk_mul_f32 v[34:35], v[34:35], v[2:3] op_sel_hi:[1,0]
	v_pk_mul_f32 v[32:33], v[32:33], v[2:3] op_sel_hi:[1,0]
	v_pk_mul_f32 v[30:31], v[30:31], v[2:3] op_sel_hi:[1,0]
	v_pk_mul_f32 v[28:29], v[28:29], v[2:3] op_sel_hi:[1,0]
	v_pk_mul_f32 v[26:27], v[26:27], v[2:3] op_sel_hi:[1,0]
	v_pk_mul_f32 v[24:25], v[24:25], v[2:3] op_sel_hi:[1,0]
	v_pk_mul_f32 v[22:23], v[22:23], v[2:3] op_sel_hi:[1,0]
	v_pk_mul_f32 v[20:21], v[20:21], v[2:3] op_sel_hi:[1,0]
	v_pk_mul_f32 v[18:19], v[18:19], v[2:3] op_sel_hi:[1,0]
	s_branch .LBB0_680
